# P8: serpentine K traversal (alternate units walk K backwards so the shared A panel tail is still L2-resident), on top of v36
# baseline (speedup 1.0000x reference)
; #define PH(n) if (ONLY < 0 || ONLY == (n))
; #define WSB(off) ((bf16*)((unsigned char*)KARG(20) + (off)))
; #define WSF(off) ((float*)((unsigned char*)KARG(20) + (off)))
; template <class Epi, class Sched>
; __device__ __forceinline__ void gemm_phase(PG8_LAS unsigned char* lds, PG8_LAS unsigned char* xl, const Gemm g, const Sched& S, const Epi& E) {
;     ...
;     Unit cur, nxt; int ui = 0;
;     if (!S.next(0, cur)) return;
; __global__ void __launch_bounds__(NWAVES * 64, 2) mk_fwd(Args args) {
;     ...
;     PH(8) { PHASE_VARS
;         pg8::Gemm g{WSB(WS_XN), WSB(WS_WGU), DM, DM, DM}; pg8::Sched2D S; S.init(T, 2 * DFF, G, bx, DM, DM);
;         pg8::EpiSwiGLU E{WSB(WS_HMID), DFF, WSF(WS_SS2)};
;         pg8::gemm_phase(lds, xl, g, S, E);
.LBB0_814:
	s_or_b64 exec, exec, s[2:3]
	s_mov_b32 s99, -1
	s_mov_b32 s84, 0
	v_mov_b32_e32 v0, v220
	s_mov_b32 s36, s39
	v_mov_b32_e32 v10, v220
	s_waitcnt lgkmcnt(0)
	s_load_dwordx2 s[2:3], s[0:1], 0xa0
	s_waitcnt lgkmcnt(0)
	s_load_dwordx2 s[8:9], s[0:1], 0xa0
	s_waitcnt lgkmcnt(0)
	s_load_dwordx2 s[12:13], s[0:1], 0xa0
	s_waitcnt lgkmcnt(0)
	s_load_dwordx2 s[6:7], s[0:1], 0xa0
	s_waitcnt lgkmcnt(0)
	s_cmpk_gt_i32 s36, 0xaff
	v_readfirstlane_b32 s18, v10
	s_cbranch_scc0 .LBB0_817
	s_and_saveexec_b64 s[2:3], s[48:49]
	s_xor_b64 s[48:49], exec, s[2:3]
	s_cbranch_execnz .LBB0_834

; #define PG8_STAGE(bufoff, gbase, voff) do { _Pragma("unroll") for (int _i = 0; _i < 2; ++_i) \
;         __builtin_amdgcn_global_load_lds((const unsigned*)((const char*)(gbase) + (voff)[_i]), (PG8_LAS unsigned*)(lds + (bufoff) + ldsw + _i * 8192), 16, 0, 0); } while (0)
; #define PG8_LDA(dst, b, h) do { _Pragma("unroll") for (int m = 0; m < 4; ++m) _Pragma("unroll") for (int k = 0; k < 2; ++k) dst[m][k] = *(const PG8_LAS bf16x8*)(lds + PG8_SA(b, h) + aoff + m * 2048 + k * 1024); } while (0)
; #define PG8_LDB(dst, b, h) do { _Pragma("unroll") for (int n = 0; n < 2; ++n) _Pragma("unroll") for (int k = 0; k < 2; ++k) dst[n][k] = *(const PG8_LAS bf16x8*)(lds + PG8_SB(b, h) + boff + n * 2048 + k * 1024); } while (0)
; #define PG8_MMA(ai, bj, At, Bt) do { __builtin_amdgcn_s_setprio(1); _Pragma("unroll") for (int m = 0; m < 4; ++m) _Pragma("unroll") for (int n = 0; n < 2; ++n) _Pragma("unroll") for (int k = 0; k < 2; ++k) \
;         acc[ai][bj][m][n] = __builtin_amdgcn_mfma_f32_16x16x32_bf16(Bt[n][k], At[m][k], acc[ai][bj][m][n], 0, 0, 0); __builtin_amdgcn_s_setprio(0); } while (0)
; #define PG8_WAIT_V(n) asm volatile("s_waitcnt vmcnt(" #n ")" ::: "memory")
; #define PG8_WAIT_L(n) asm volatile("s_waitcnt lgkmcnt(" #n ")" ::: "memory")
; #define PG8_BAR __builtin_amdgcn_s_barrier()
; #define PG8_SCHED __builtin_amdgcn_sched_barrier(0)
; template <class Epi, class Sched>
; __device__ __forceinline__ void gemm_phase(PG8_LAS unsigned char* lds, PG8_LAS unsigned char* xl, const Gemm g, const Sched& S, const Epi& E) {
;     ...
;         const char* nA = has_next ? (const char*)g.A + nxt.aoff : cA; const char* nB = has_next ? (const char*)g.Bt + nxt.boff : cB;
; #pragma unroll 1
;         for (int t = 0; t < nt; t += 2) {
;             const bool last = (t == nt - 2);
;             const char* a1 = cA + (size_t)(t + 1) * kstep;
;             const char* a2 = last ? nA : cA + (size_t)(t + 2) * kstep; const char* b2 = last ? nB : cB + (size_t)(t + 2) * kstep;
;             const char* a3 = a2 + kstep; const char* b3 = b2 + kstep;
;             PG8_LDB(B0, 0, 0); PG8_LDB(B1, 0, 1); PG8_SCHED; PG8_LDA(At, 0, 0); PG8_STAGE(PG8_SA(1, 1), a1 + hsA, voffA);
;             PG8_WAIT_V(8); PG8_WAIT_L(0); PG8_BAR; PG8_MMA(0, 0, At, B0); PG8_MMA(0, 1, At, B1); PG8_BAR; PG8_SCHED;
.LBB0_824:
	s_add_u32 s26, s37, s20
	s_addc_u32 s27, s42, s21
	s_xor_b32 s85, s84, 1
	s_mulk_i32 s85, 0x700
	s_add_u32 s26, s26, s85
	s_addc_u32 s27, s27, 0
	s_and_b64 s[28:29], s[6:7], exec
	s_cselect_b32 s46, s27, s31
	s_cselect_b32 s47, s26, s30
	s_add_u32 s28, s43, s22
	s_addc_u32 s29, s50, s23
	s_add_u32 s28, s28, s85
	s_addc_u32 s29, s29, 0
	s_and_b64 s[34:35], s[6:7], exec
	s_cselect_b32 s70, s29, s3
	s_cselect_b32 s72, s28, s2
	s_lshl_b32 s80, s84, 9
	s_sub_u32 s80, 0x100, s80
	s_sub_u32 s81, 0, s84
	s_add_u32 s82, s80, 0xfffbff80
	s_addc_u32 s83, s81, -1
	s_add_u32 s73, s2, s80
	s_addc_u32 s74, s3, s81
	s_add_u32 s2, s30, 0x40080
	v_mov_b32_e32 v0, 0
	s_addc_u32 s3, s31, 0
	s_mov_b32 s75, -2
	s_xor_b32 s84, s84, 1
	v_mov_b32_e32 v1, v0
	v_mov_b32_e32 v2, v0
	v_mov_b32_e32 v3, v0
	v_mov_b32_e32 v8, v0
	v_mov_b32_e32 v9, v0
	v_mov_b32_e32 v10, v0
	v_mov_b32_e32 v11, v0
	v_mov_b32_e32 v16, v0
	v_mov_b32_e32 v17, v0
	v_mov_b32_e32 v18, v0
	v_mov_b32_e32 v19, v0
	v_mov_b32_e32 v24, v0
	v_mov_b32_e32 v25, v0
	v_mov_b32_e32 v26, v0
	v_mov_b32_e32 v27, v0
	v_mov_b32_e32 v32, v0
	v_mov_b32_e32 v33, v0
	v_mov_b32_e32 v34, v0
	v_mov_b32_e32 v35, v0
	v_mov_b32_e32 v40, v0
	v_mov_b32_e32 v41, v0
	v_mov_b32_e32 v42, v0
	v_mov_b32_e32 v43, v0
	v_mov_b32_e32 v48, v0
	v_mov_b32_e32 v49, v0
	v_mov_b32_e32 v50, v0
	v_mov_b32_e32 v51, v0
	v_mov_b32_e32 v56, v0
	v_mov_b32_e32 v57, v0
	v_mov_b32_e32 v58, v0
	v_mov_b32_e32 v59, v0
	v_mov_b32_e32 v4, v0
	v_mov_b32_e32 v5, v0
	v_mov_b32_e32 v6, v0
	v_mov_b32_e32 v7, v0
	v_mov_b32_e32 v12, v0
	v_mov_b32_e32 v13, v0
	v_mov_b32_e32 v14, v0
	v_mov_b32_e32 v15, v0
	v_mov_b32_e32 v20, v0
	v_mov_b32_e32 v21, v0
	v_mov_b32_e32 v22, v0
	v_mov_b32_e32 v23, v0
	v_mov_b32_e32 v28, v0
	v_mov_b32_e32 v29, v0
	v_mov_b32_e32 v30, v0
	v_mov_b32_e32 v31, v0
	v_mov_b32_e32 v36, v0
	v_mov_b32_e32 v37, v0
	v_mov_b32_e32 v38, v0
	v_mov_b32_e32 v39, v0
	v_mov_b32_e32 v44, v0
	v_mov_b32_e32 v45, v0
	v_mov_b32_e32 v46, v0
	v_mov_b32_e32 v47, v0
	v_mov_b32_e32 v52, v0
	v_mov_b32_e32 v53, v0
	v_mov_b32_e32 v54, v0
	v_mov_b32_e32 v55, v0
	v_mov_b32_e32 v60, v0
	v_mov_b32_e32 v61, v0
	v_mov_b32_e32 v62, v0
	v_mov_b32_e32 v63, v0
	v_mov_b32_e32 v64, v0
	v_mov_b32_e32 v65, v0
	v_mov_b32_e32 v66, v0
	v_mov_b32_e32 v67, v0
	v_mov_b32_e32 v72, v0
	v_mov_b32_e32 v73, v0
	v_mov_b32_e32 v74, v0
	v_mov_b32_e32 v75, v0
	v_mov_b32_e32 v80, v0
	v_mov_b32_e32 v81, v0
	v_mov_b32_e32 v82, v0
	v_mov_b32_e32 v83, v0
	v_mov_b32_e32 v88, v0
	v_mov_b32_e32 v89, v0
	v_mov_b32_e32 v90, v0
	v_mov_b32_e32 v91, v0
	v_mov_b32_e32 v96, v0
	v_mov_b32_e32 v97, v0
	v_mov_b32_e32 v98, v0
	v_mov_b32_e32 v99, v0
	s_nop 0
	v_mov_b32_e32 v104, v0
	v_mov_b32_e32 v105, v0
	v_mov_b32_e32 v106, v0
	v_mov_b32_e32 v107, v0
	v_mov_b32_e32 v112, v0
	v_mov_b32_e32 v113, v0
	v_mov_b32_e32 v114, v0
	v_mov_b32_e32 v115, v0
	v_mov_b32_e32 v120, v0
	v_mov_b32_e32 v121, v0
	v_mov_b32_e32 v122, v0
	v_mov_b32_e32 v123, v0
	v_mov_b32_e32 v68, v0
	v_mov_b32_e32 v69, v0
	v_mov_b32_e32 v70, v0
	v_mov_b32_e32 v71, v0
	v_mov_b32_e32 v76, v0
	v_mov_b32_e32 v77, v0
	v_mov_b32_e32 v78, v0
	v_mov_b32_e32 v79, v0
	v_mov_b32_e32 v84, v0
	v_mov_b32_e32 v85, v0
	v_mov_b32_e32 v86, v0
	v_mov_b32_e32 v87, v0
	v_mov_b32_e32 v92, v0
	v_mov_b32_e32 v93, v0
	v_mov_b32_e32 v94, v0
	v_mov_b32_e32 v95, v0
	v_mov_b32_e32 v100, v0
	v_mov_b32_e32 v101, v0
	v_mov_b32_e32 v102, v0
	v_mov_b32_e32 v103, v0
	v_mov_b32_e32 v108, v0
	v_mov_b32_e32 v109, v0
	v_mov_b32_e32 v110, v0
	v_mov_b32_e32 v111, v0
	v_mov_b32_e32 v116, v0
	v_mov_b32_e32 v117, v0
	v_mov_b32_e32 v118, v0
	v_mov_b32_e32 v119, v0
	v_mov_b32_e32 v124, v0
	v_mov_b32_e32 v125, v0
	v_mov_b32_e32 v126, v0
	v_mov_b32_e32 v127, v0
.LBB0_825:
	ds_read_b128 v[170:173], v164
	ds_read_b128 v[174:177], v164 offset:1024
	ds_read_b128 v[180:183], v164 offset:2048
	ds_read_b128 v[184:187], v164 offset:3072
	ds_read_b128 v[188:191], v165
	ds_read_b128 v[192:195], v165 offset:1024
	ds_read_b128 v[196:199], v165 offset:2048
	ds_read_b128 v[200:203], v165 offset:3072
	s_add_u32 s30, s2, s82
	s_addc_u32 s31, s3, s83
	s_cmp_eq_u32 s75, 12
	s_cselect_b32 s35, s46, s31
	s_cselect_b32 s34, s47, s30
	s_cselect_b32 s31, s70, s74
	s_cselect_b32 s30, s72, s73
	v_lshl_add_u64 v[238:239], s[2:3], 0, v[140:141]
	s_add_i32 m0, s55, 0xc000
	ds_read_b128 v[204:207], v166
	ds_read_b128 v[208:211], v166 offset:1024
	ds_read_b128 v[212:215], v166 offset:2048
	ds_read_b128 v[216:219], v166 offset:3072
	ds_read_b128 v[222:225], v166 offset:4096
	ds_read_b128 v[226:229], v166 offset:5120
	ds_read_b128 v[230:233], v166 offset:6144
	ds_read_b128 v[234:237], v166 offset:7168
	global_load_lds_dwordx4 v[238:239], off
	v_lshl_add_u64 v[238:239], s[2:3], 0, v[138:139]
	s_add_i32 m0, s55, 0xe000
	s_nop 0
	global_load_lds_dwordx4 v[238:239], off
	s_waitcnt vmcnt(8)
	s_waitcnt lgkmcnt(0)
	s_barrier
; #define PG8_STAGE(bufoff, gbase, voff) do { _Pragma("unroll") for (int _i = 0; _i < 2; ++_i) \
;         __builtin_amdgcn_global_load_lds((const unsigned*)((const char*)(gbase) + (voff)[_i]), (PG8_LAS unsigned*)(lds + (bufoff) + ldsw + _i * 8192), 16, 0, 0); } while (0)
; #define PG8_LDA(dst, b, h) do { _Pragma("unroll") for (int m = 0; m < 4; ++m) _Pragma("unroll") for (int k = 0; k < 2; ++k) dst[m][k] = *(const PG8_LAS bf16x8*)(lds + PG8_SA(b, h) + aoff + m * 2048 + k * 1024); } while (0)
; #define PG8_MMA(ai, bj, At, Bt) do { __builtin_amdgcn_s_setprio(1); _Pragma("unroll") for (int m = 0; m < 4; ++m) _Pragma("unroll") for (int n = 0; n < 2; ++n) _Pragma("unroll") for (int k = 0; k < 2; ++k) \
;         acc[ai][bj][m][n] = __builtin_amdgcn_mfma_f32_16x16x32_bf16(Bt[n][k], At[m][k], acc[ai][bj][m][n], 0, 0, 0); __builtin_amdgcn_s_setprio(0); } while (0)
; #define PG8_WAIT_V(n) asm volatile("s_waitcnt vmcnt(" #n ")" ::: "memory")
; #define PG8_WAIT_L(n) asm volatile("s_waitcnt lgkmcnt(" #n ")" ::: "memory")
; #define PG8_BAR __builtin_amdgcn_s_barrier()
; #define PG8_SCHED __builtin_amdgcn_sched_barrier(0)
; template <class Epi, class Sched>
; __device__ __forceinline__ void gemm_phase(PG8_LAS unsigned char* lds, PG8_LAS unsigned char* xl, const Gemm g, const Sched& S, const Epi& E) {
;     ...
;             PG8_WAIT_V(8); PG8_WAIT_L(0); PG8_BAR; PG8_MMA(0, 0, At, B0); PG8_MMA(0, 1, At, B1); PG8_BAR; PG8_SCHED;
;             PG8_LDA(At, 0, 1); PG8_STAGE(PG8_SB(0, 0), b2, voffB); PG8_STAGE(PG8_SB(0, 1), b2 + hsB, voffB); PG8_STAGE(PG8_SA(0, 0), a2, voffA);
;             PG8_WAIT_V(8); PG8_WAIT_L(0); PG8_BAR; PG8_MMA(1, 0, At, B0); PG8_MMA(1, 1, At, B1); PG8_BAR; PG8_SCHED;
	s_setprio 1
	s_waitcnt lgkmcnt(0)
	v_mfma_f32_16x16x32_bf16 v[124:127], v[170:173], v[204:207], v[124:127]
	v_mfma_f32_16x16x32_bf16 v[116:119], v[180:183], v[204:207], v[116:119]
	v_mfma_f32_16x16x32_bf16 v[108:111], v[170:173], v[212:215], v[108:111]
	v_mfma_f32_16x16x32_bf16 v[100:103], v[180:183], v[212:215], v[100:103]
	v_mfma_f32_16x16x32_bf16 v[92:95], v[170:173], v[222:225], v[92:95]
	v_mfma_f32_16x16x32_bf16 v[84:87], v[180:183], v[222:225], v[84:87]
	v_mfma_f32_16x16x32_bf16 v[76:79], v[170:173], v[230:233], v[76:79]
	v_mfma_f32_16x16x32_bf16 v[68:71], v[180:183], v[230:233], v[68:71]
	v_mfma_f32_16x16x32_bf16 v[124:127], v[174:177], v[208:211], v[124:127]
	v_mfma_f32_16x16x32_bf16 v[116:119], v[184:187], v[208:211], v[116:119]
	v_mfma_f32_16x16x32_bf16 v[108:111], v[174:177], v[216:219], v[108:111]
	v_mfma_f32_16x16x32_bf16 v[100:103], v[184:187], v[216:219], v[100:103]
	v_mfma_f32_16x16x32_bf16 v[92:95], v[174:177], v[226:229], v[92:95]
	v_mfma_f32_16x16x32_bf16 v[84:87], v[184:187], v[226:229], v[84:87]
	v_mfma_f32_16x16x32_bf16 v[76:79], v[174:177], v[234:237], v[76:79]
	v_mfma_f32_16x16x32_bf16 v[68:71], v[184:187], v[234:237], v[68:71]
	s_setprio 0
	s_setprio 1
	v_mfma_f32_16x16x32_bf16 v[120:123], v[188:191], v[204:207], v[120:123]
	v_mfma_f32_16x16x32_bf16 v[112:115], v[196:199], v[204:207], v[112:115]
	v_mfma_f32_16x16x32_bf16 v[104:107], v[188:191], v[212:215], v[104:107]
	v_mfma_f32_16x16x32_bf16 v[96:99], v[196:199], v[212:215], v[96:99]
	v_mfma_f32_16x16x32_bf16 v[88:91], v[188:191], v[222:225], v[88:91]
	v_mfma_f32_16x16x32_bf16 v[80:83], v[196:199], v[222:225], v[80:83]
	v_mfma_f32_16x16x32_bf16 v[72:75], v[188:191], v[230:233], v[72:75]
	v_mfma_f32_16x16x32_bf16 v[64:67], v[196:199], v[230:233], v[64:67]
	v_mfma_f32_16x16x32_bf16 v[120:123], v[192:195], v[208:211], v[120:123]
	v_mfma_f32_16x16x32_bf16 v[112:115], v[200:203], v[208:211], v[112:115]
	v_mfma_f32_16x16x32_bf16 v[104:107], v[192:195], v[216:219], v[104:107]
	v_mfma_f32_16x16x32_bf16 v[96:99], v[200:203], v[216:219], v[96:99]
	v_mfma_f32_16x16x32_bf16 v[88:91], v[192:195], v[226:229], v[88:91]
	v_mfma_f32_16x16x32_bf16 v[80:83], v[200:203], v[226:229], v[80:83]
	v_mfma_f32_16x16x32_bf16 v[72:75], v[192:195], v[234:237], v[72:75]
	v_mfma_f32_16x16x32_bf16 v[64:67], v[200:203], v[234:237], v[64:67]
	s_setprio 0
	s_barrier
	s_add_i32 s68, s54, s51
	v_lshl_add_u64 v[238:239], s[30:31], 0, v[132:133]
	s_mov_b32 m0, s68
	ds_read_b128 v[204:207], v166 offset:16384
	ds_read_b128 v[208:211], v166 offset:17408
	ds_read_b128 v[212:215], v166 offset:18432
	ds_read_b128 v[216:219], v166 offset:19456
	ds_read_b128 v[222:225], v166 offset:20480
	ds_read_b128 v[226:229], v166 offset:21504
	ds_read_b128 v[230:233], v166 offset:22528
	ds_read_b128 v[234:237], v166 offset:23552
	global_load_lds_dwordx4 v[238:239], off
	s_add_i32 m0, s68, 0x2000
	s_add_u32 s76, s30, 0x40000
	v_lshl_add_u64 v[240:241], s[30:31], 0, v[128:129]
	s_addc_u32 s77, s31, 0
	s_add_i32 s68, s62, s51
	global_load_lds_dwordx4 v[240:241], off
	v_lshl_add_u64 v[242:243], s[76:77], 0, v[132:133]
	s_mov_b32 m0, s68
	v_lshl_add_u64 v[244:245], s[34:35], 0, v[130:131]
	global_load_lds_dwordx4 v[242:243], off
	v_lshl_add_u64 v[242:243], s[76:77], 0, v[128:129]
	s_add_i32 m0, s68, 0x2000
	s_nop 0
	global_load_lds_dwordx4 v[242:243], off
	v_lshl_add_u64 v[242:243], s[34:35], 0, v[134:135]
	s_mov_b32 m0, s55
	s_nop 0
	global_load_lds_dwordx4 v[242:243], off
	s_mov_b32 m0, s56
	s_nop 0
	global_load_lds_dwordx4 v[244:245], off
	s_waitcnt vmcnt(8)
	s_waitcnt lgkmcnt(0)
	s_barrier
	s_setprio 1
	s_waitcnt lgkmcnt(0)
	v_mfma_f32_16x16x32_bf16 v[60:63], v[170:173], v[204:207], v[60:63]
	v_mfma_f32_16x16x32_bf16 v[52:55], v[180:183], v[204:207], v[52:55]
	v_mfma_f32_16x16x32_bf16 v[44:47], v[170:173], v[212:215], v[44:47]
	v_mfma_f32_16x16x32_bf16 v[36:39], v[180:183], v[212:215], v[36:39]
	v_mfma_f32_16x16x32_bf16 v[28:31], v[170:173], v[222:225], v[28:31]
	v_mfma_f32_16x16x32_bf16 v[20:23], v[180:183], v[222:225], v[20:23]
	v_mfma_f32_16x16x32_bf16 v[12:15], v[170:173], v[230:233], v[12:15]
	v_mfma_f32_16x16x32_bf16 v[4:7], v[180:183], v[230:233], v[4:7]
	v_mfma_f32_16x16x32_bf16 v[60:63], v[174:177], v[208:211], v[60:63]
	v_mfma_f32_16x16x32_bf16 v[52:55], v[184:187], v[208:211], v[52:55]
	v_mfma_f32_16x16x32_bf16 v[44:47], v[174:177], v[216:219], v[44:47]
	v_mfma_f32_16x16x32_bf16 v[36:39], v[184:187], v[216:219], v[36:39]
	v_mfma_f32_16x16x32_bf16 v[28:31], v[174:177], v[226:229], v[28:31]
	v_mfma_f32_16x16x32_bf16 v[20:23], v[184:187], v[226:229], v[20:23]
	v_mfma_f32_16x16x32_bf16 v[12:15], v[174:177], v[234:237], v[12:15]
	v_mfma_f32_16x16x32_bf16 v[4:7], v[184:187], v[234:237], v[4:7]
	s_setprio 0
	s_setprio 1
	v_mfma_f32_16x16x32_bf16 v[56:59], v[188:191], v[204:207], v[56:59]
	v_mfma_f32_16x16x32_bf16 v[48:51], v[196:199], v[204:207], v[48:51]
	v_mfma_f32_16x16x32_bf16 v[40:43], v[188:191], v[212:215], v[40:43]
	v_mfma_f32_16x16x32_bf16 v[32:35], v[196:199], v[212:215], v[32:35]
	v_mfma_f32_16x16x32_bf16 v[24:27], v[188:191], v[222:225], v[24:27]
	v_mfma_f32_16x16x32_bf16 v[16:19], v[196:199], v[222:225], v[16:19]
	v_mfma_f32_16x16x32_bf16 v[8:11], v[188:191], v[230:233], v[8:11]
	v_mfma_f32_16x16x32_bf16 v[0:3], v[196:199], v[230:233], v[0:3]
	v_mfma_f32_16x16x32_bf16 v[56:59], v[192:195], v[208:211], v[56:59]
	v_mfma_f32_16x16x32_bf16 v[48:51], v[200:203], v[208:211], v[48:51]
	v_mfma_f32_16x16x32_bf16 v[40:43], v[192:195], v[216:219], v[40:43]
	v_mfma_f32_16x16x32_bf16 v[32:35], v[200:203], v[216:219], v[32:35]
	v_mfma_f32_16x16x32_bf16 v[24:27], v[192:195], v[226:229], v[24:27]
	v_mfma_f32_16x16x32_bf16 v[16:19], v[200:203], v[226:229], v[16:19]
	v_mfma_f32_16x16x32_bf16 v[8:11], v[192:195], v[234:237], v[8:11]
	v_mfma_f32_16x16x32_bf16 v[0:3], v[200:203], v[234:237], v[0:3]
	s_setprio 0
	s_barrier
; #define PG8_STAGE(bufoff, gbase, voff) do { _Pragma("unroll") for (int _i = 0; _i < 2; ++_i) \
;         __builtin_amdgcn_global_load_lds((const unsigned*)((const char*)(gbase) + (voff)[_i]), (PG8_LAS unsigned*)(lds + (bufoff) + ldsw + _i * 8192), 16, 0, 0); } while (0)
; #define PG8_LDA(dst, b, h) do { _Pragma("unroll") for (int m = 0; m < 4; ++m) _Pragma("unroll") for (int k = 0; k < 2; ++k) dst[m][k] = *(const PG8_LAS bf16x8*)(lds + PG8_SA(b, h) + aoff + m * 2048 + k * 1024); } while (0)
; #define PG8_LDB(dst, b, h) do { _Pragma("unroll") for (int n = 0; n < 2; ++n) _Pragma("unroll") for (int k = 0; k < 2; ++k) dst[n][k] = *(const PG8_LAS bf16x8*)(lds + PG8_SB(b, h) + boff + n * 2048 + k * 1024); } while (0)
; #define PG8_MMA(ai, bj, At, Bt) do { __builtin_amdgcn_s_setprio(1); _Pragma("unroll") for (int m = 0; m < 4; ++m) _Pragma("unroll") for (int n = 0; n < 2; ++n) _Pragma("unroll") for (int k = 0; k < 2; ++k) \
;         acc[ai][bj][m][n] = __builtin_amdgcn_mfma_f32_16x16x32_bf16(Bt[n][k], At[m][k], acc[ai][bj][m][n], 0, 0, 0); __builtin_amdgcn_s_setprio(0); } while (0)
; #define PG8_WAIT_V(n) asm volatile("s_waitcnt vmcnt(" #n ")" ::: "memory")
; #define PG8_WAIT_L(n) asm volatile("s_waitcnt lgkmcnt(" #n ")" ::: "memory")
; #define PG8_BAR __builtin_amdgcn_s_barrier()
; #define PG8_SCHED __builtin_amdgcn_sched_barrier(0)
; template <class Epi, class Sched>
; __device__ __forceinline__ void gemm_phase(PG8_LAS unsigned char* lds, PG8_LAS unsigned char* xl, const Gemm g, const Sched& S, const Epi& E) {
;     ...
;             PG8_LDB(B0, 1, 0); PG8_LDB(B1, 1, 1); PG8_SCHED; PG8_LDA(At, 1, 0); PG8_STAGE(PG8_SA(0, 1), a2 + hsA, voffA);
;             PG8_WAIT_V(8); PG8_WAIT_L(0); PG8_BAR; PG8_MMA(0, 0, At, B0); PG8_MMA(0, 1, At, B1); PG8_BAR; PG8_SCHED;
	s_add_i32 s68, 0, 0x18000
	v_add_u32_e32 v169, s68, v147
	s_add_i32 s76, 0, 0x1c000
	ds_read_b128 v[170:173], v169
	ds_read_b128 v[174:177], v169 offset:1024
	ds_read_b128 v[180:183], v169 offset:2048
	ds_read_b128 v[184:187], v169 offset:3072
	v_add_u32_e32 v169, s76, v147
	ds_read_b128 v[188:191], v169
	ds_read_b128 v[192:195], v169 offset:1024
	ds_read_b128 v[196:199], v169 offset:2048
	ds_read_b128 v[200:203], v169 offset:3072
	s_add_u32 s34, s34, 0x40000
	s_addc_u32 s35, s35, 0
	s_mov_b32 m0, s57
	v_lshl_add_u64 v[246:247], s[34:35], 0, v[134:135]
	ds_read_b128 v[204:207], v166 offset:32768
	ds_read_b128 v[208:211], v166 offset:33792
	ds_read_b128 v[212:215], v166 offset:34816
	ds_read_b128 v[216:219], v166 offset:35840
	ds_read_b128 v[222:225], v166 offset:36864
	ds_read_b128 v[226:229], v166 offset:37888
	ds_read_b128 v[230:233], v166 offset:38912
	ds_read_b128 v[234:237], v166 offset:39936
	global_load_lds_dwordx4 v[246:247], off
	v_lshl_add_u64 v[246:247], s[34:35], 0, v[130:131]
	s_mov_b32 m0, s58
	s_nop 0
	global_load_lds_dwordx4 v[246:247], off
	s_waitcnt vmcnt(8)
	s_waitcnt lgkmcnt(0)
	s_barrier
	s_setprio 1
	s_waitcnt lgkmcnt(0)
	v_mfma_f32_16x16x32_bf16 v[124:127], v[170:173], v[204:207], v[124:127]
	v_mfma_f32_16x16x32_bf16 v[116:119], v[180:183], v[204:207], v[116:119]
	v_mfma_f32_16x16x32_bf16 v[108:111], v[170:173], v[212:215], v[108:111]
	v_mfma_f32_16x16x32_bf16 v[100:103], v[180:183], v[212:215], v[100:103]
	v_mfma_f32_16x16x32_bf16 v[92:95], v[170:173], v[222:225], v[92:95]
	v_mfma_f32_16x16x32_bf16 v[84:87], v[180:183], v[222:225], v[84:87]
	v_mfma_f32_16x16x32_bf16 v[76:79], v[170:173], v[230:233], v[76:79]
	v_mfma_f32_16x16x32_bf16 v[68:71], v[180:183], v[230:233], v[68:71]
	v_mfma_f32_16x16x32_bf16 v[124:127], v[174:177], v[208:211], v[124:127]
	v_mfma_f32_16x16x32_bf16 v[116:119], v[184:187], v[208:211], v[116:119]
	v_mfma_f32_16x16x32_bf16 v[108:111], v[174:177], v[216:219], v[108:111]
	v_mfma_f32_16x16x32_bf16 v[100:103], v[184:187], v[216:219], v[100:103]
	v_mfma_f32_16x16x32_bf16 v[92:95], v[174:177], v[226:229], v[92:95]
	v_mfma_f32_16x16x32_bf16 v[84:87], v[184:187], v[226:229], v[84:87]
	v_mfma_f32_16x16x32_bf16 v[76:79], v[174:177], v[234:237], v[76:79]
	v_mfma_f32_16x16x32_bf16 v[68:71], v[184:187], v[234:237], v[68:71]
	s_setprio 0
	s_setprio 1
	v_mfma_f32_16x16x32_bf16 v[120:123], v[188:191], v[204:207], v[120:123]
	v_mfma_f32_16x16x32_bf16 v[112:115], v[196:199], v[204:207], v[112:115]
	v_mfma_f32_16x16x32_bf16 v[104:107], v[188:191], v[212:215], v[104:107]
	v_mfma_f32_16x16x32_bf16 v[96:99], v[196:199], v[212:215], v[96:99]
	v_mfma_f32_16x16x32_bf16 v[88:91], v[188:191], v[222:225], v[88:91]
	v_mfma_f32_16x16x32_bf16 v[80:83], v[196:199], v[222:225], v[80:83]
	v_mfma_f32_16x16x32_bf16 v[72:75], v[188:191], v[230:233], v[72:75]
	v_mfma_f32_16x16x32_bf16 v[64:67], v[196:199], v[230:233], v[64:67]
	v_mfma_f32_16x16x32_bf16 v[120:123], v[192:195], v[208:211], v[120:123]
	v_mfma_f32_16x16x32_bf16 v[112:115], v[200:203], v[208:211], v[112:115]
	v_mfma_f32_16x16x32_bf16 v[104:107], v[192:195], v[216:219], v[104:107]
	v_mfma_f32_16x16x32_bf16 v[96:99], v[200:203], v[216:219], v[96:99]
	v_mfma_f32_16x16x32_bf16 v[88:91], v[192:195], v[226:229], v[88:91]
	v_mfma_f32_16x16x32_bf16 v[80:83], v[200:203], v[226:229], v[80:83]
	v_mfma_f32_16x16x32_bf16 v[72:75], v[192:195], v[234:237], v[72:75]
	v_mfma_f32_16x16x32_bf16 v[64:67], v[200:203], v[234:237], v[64:67]
	s_setprio 0
	s_barrier
; #define PG8_STAGE(bufoff, gbase, voff) do { _Pragma("unroll") for (int _i = 0; _i < 2; ++_i) \
;         __builtin_amdgcn_global_load_lds((const unsigned*)((const char*)(gbase) + (voff)[_i]), (PG8_LAS unsigned*)(lds + (bufoff) + ldsw + _i * 8192), 16, 0, 0); } while (0)
; #define PG8_LDA(dst, b, h) do { _Pragma("unroll") for (int m = 0; m < 4; ++m) _Pragma("unroll") for (int k = 0; k < 2; ++k) dst[m][k] = *(const PG8_LAS bf16x8*)(lds + PG8_SA(b, h) + aoff + m * 2048 + k * 1024); } while (0)
; #define PG8_MMA(ai, bj, At, Bt) do { __builtin_amdgcn_s_setprio(1); _Pragma("unroll") for (int m = 0; m < 4; ++m) _Pragma("unroll") for (int n = 0; n < 2; ++n) _Pragma("unroll") for (int k = 0; k < 2; ++k) \
;         acc[ai][bj][m][n] = __builtin_amdgcn_mfma_f32_16x16x32_bf16(Bt[n][k], At[m][k], acc[ai][bj][m][n], 0, 0, 0); __builtin_amdgcn_s_setprio(0); } while (0)
; #define PG8_WAIT_V(n) asm volatile("s_waitcnt vmcnt(" #n ")" ::: "memory")
; #define PG8_WAIT_L(n) asm volatile("s_waitcnt lgkmcnt(" #n ")" ::: "memory")
; #define PG8_BAR __builtin_amdgcn_s_barrier()
; #define PG8_SCHED __builtin_amdgcn_sched_barrier(0)
; template <class Epi, class Sched>
; __device__ __forceinline__ void gemm_phase(PG8_LAS unsigned char* lds, PG8_LAS unsigned char* xl, const Gemm g, const Sched& S, const Epi& E) {
;     ...
;             PG8_LDA(At, 1, 1); PG8_STAGE(PG8_SB(1, 0), b3, voffB); PG8_STAGE(PG8_SB(1, 1), b3 + hsB, voffB); PG8_STAGE(PG8_SA(1, 0), a3, voffA);
;             PG8_WAIT_V(8); PG8_WAIT_L(0); PG8_BAR; PG8_MMA(1, 0, At, B0); PG8_MMA(1, 1, At, B1); PG8_BAR; PG8_SCHED;
;         }
	s_add_i32 s34, s68, s51
	v_lshl_add_u64 v[238:239], v[238:239], 0, s[16:17]
	s_mov_b32 m0, s34
	ds_read_b128 v[204:207], v166 offset:49152
	ds_read_b128 v[208:211], v166 offset:50176
	ds_read_b128 v[212:215], v166 offset:51200
	ds_read_b128 v[216:219], v166 offset:52224
	ds_read_b128 v[222:225], v166 offset:53248
	ds_read_b128 v[226:229], v166 offset:54272
	ds_read_b128 v[230:233], v166 offset:55296
	ds_read_b128 v[234:237], v166 offset:56320
	global_load_lds_dwordx4 v[238:239], off
	s_add_i32 m0, s34, 0x2000
	s_add_u32 s30, s30, 0x40080
	v_lshl_add_u64 v[238:239], v[240:241], 0, s[16:17]
	s_addc_u32 s31, s31, 0
	s_add_i32 s34, s76, s51
	global_load_lds_dwordx4 v[238:239], off
	v_lshl_add_u64 v[238:239], s[30:31], 0, v[132:133]
	s_mov_b32 m0, s34
	s_nop 0
	global_load_lds_dwordx4 v[238:239], off
	v_lshl_add_u64 v[238:239], s[30:31], 0, v[128:129]
	s_add_i32 m0, s34, 0x2000
	s_nop 0
	global_load_lds_dwordx4 v[238:239], off
	v_lshl_add_u64 v[238:239], v[242:243], 0, s[16:17]
	s_mov_b32 m0, s59
	s_nop 0
	global_load_lds_dwordx4 v[238:239], off
	v_lshl_add_u64 v[238:239], v[244:245], 0, s[16:17]
	s_mov_b32 m0, s61
	s_nop 0
	global_load_lds_dwordx4 v[238:239], off
	s_waitcnt vmcnt(8)
	s_waitcnt lgkmcnt(0)
	s_barrier
	s_setprio 1
	s_waitcnt lgkmcnt(0)
	v_mfma_f32_16x16x32_bf16 v[60:63], v[170:173], v[204:207], v[60:63]
	v_mfma_f32_16x16x32_bf16 v[52:55], v[180:183], v[204:207], v[52:55]
	v_mfma_f32_16x16x32_bf16 v[44:47], v[170:173], v[212:215], v[44:47]
	v_mfma_f32_16x16x32_bf16 v[36:39], v[180:183], v[212:215], v[36:39]
	v_mfma_f32_16x16x32_bf16 v[28:31], v[170:173], v[222:225], v[28:31]
	v_mfma_f32_16x16x32_bf16 v[20:23], v[180:183], v[222:225], v[20:23]
	v_mfma_f32_16x16x32_bf16 v[12:15], v[170:173], v[230:233], v[12:15]
	v_mfma_f32_16x16x32_bf16 v[4:7], v[180:183], v[230:233], v[4:7]
	v_mfma_f32_16x16x32_bf16 v[60:63], v[174:177], v[208:211], v[60:63]
	v_mfma_f32_16x16x32_bf16 v[52:55], v[184:187], v[208:211], v[52:55]
	v_mfma_f32_16x16x32_bf16 v[44:47], v[174:177], v[216:219], v[44:47]
	v_mfma_f32_16x16x32_bf16 v[36:39], v[184:187], v[216:219], v[36:39]
	v_mfma_f32_16x16x32_bf16 v[28:31], v[174:177], v[226:229], v[28:31]
	v_mfma_f32_16x16x32_bf16 v[20:23], v[184:187], v[226:229], v[20:23]
	v_mfma_f32_16x16x32_bf16 v[12:15], v[174:177], v[234:237], v[12:15]
	v_mfma_f32_16x16x32_bf16 v[4:7], v[184:187], v[234:237], v[4:7]
	s_setprio 0
	s_setprio 1
	v_mfma_f32_16x16x32_bf16 v[56:59], v[188:191], v[204:207], v[56:59]
	v_mfma_f32_16x16x32_bf16 v[48:51], v[196:199], v[204:207], v[48:51]
	v_mfma_f32_16x16x32_bf16 v[40:43], v[188:191], v[212:215], v[40:43]
	v_mfma_f32_16x16x32_bf16 v[32:35], v[196:199], v[212:215], v[32:35]
	v_mfma_f32_16x16x32_bf16 v[24:27], v[188:191], v[222:225], v[24:27]
	v_mfma_f32_16x16x32_bf16 v[16:19], v[196:199], v[222:225], v[16:19]
	v_mfma_f32_16x16x32_bf16 v[8:11], v[188:191], v[230:233], v[8:11]
	v_mfma_f32_16x16x32_bf16 v[0:3], v[196:199], v[230:233], v[0:3]
	v_mfma_f32_16x16x32_bf16 v[56:59], v[192:195], v[208:211], v[56:59]
	v_mfma_f32_16x16x32_bf16 v[48:51], v[200:203], v[208:211], v[48:51]
	v_mfma_f32_16x16x32_bf16 v[40:43], v[192:195], v[216:219], v[40:43]
	v_mfma_f32_16x16x32_bf16 v[32:35], v[200:203], v[216:219], v[32:35]
	v_mfma_f32_16x16x32_bf16 v[24:27], v[192:195], v[226:229], v[24:27]
	v_mfma_f32_16x16x32_bf16 v[16:19], v[200:203], v[226:229], v[16:19]
	v_mfma_f32_16x16x32_bf16 v[8:11], v[192:195], v[234:237], v[8:11]
	v_mfma_f32_16x16x32_bf16 v[0:3], v[200:203], v[234:237], v[0:3]
	s_setprio 0
	s_barrier
	s_add_i32 s75, s75, 2
	s_add_u32 s73, s73, s80
	s_addc_u32 s74, s74, s81
	s_add_u32 s2, s2, s80
	s_addc_u32 s3, s3, s81
	s_cmp_gt_u32 s75, 13
	s_cbranch_scc0 .LBB0_825
	s_and_b64 vcc, exec, s[18:19]
	s_cbranch_vccz .LBB0_828
	s_barrier
